# DSA_IN indexer-Q/indexer-K rope epilogues rewritten: 16 table loads up front + counted vmcnt (were 32/16 serialized load->wait->store round trips on the phase's critical XCDs)
# speedup vs baseline: 1.0160x; 1.0160x over previous
; DI bf16 f2bf(float a) { return (bf16)(pack2(a, 0.f) & 0xffffu); }
; DI int crow(int i, int g) { return (i & 3) + 8 * (i >> 2) + 4 * g; }
;     ...
;       } else {
;         bf16* ki = (bf16*)(ws + OFF_KI);
;         float* wi = (float*)(ws + OFF_WI);
; #pragma unroll
;         for (int i = 0; i < 16; ++i) {
;           int rl = 32 * w + crow(i, g);
;           int s = (m0 & 2047) + rl;
;           float2 cs = t64[s * 32 + r];
;           float x1 = acc[0][i], x2 = acc[1][i];
;           bf16* kp = ki + (size_t)(m0 + rl) * 64;
;           kp[r] = f2bf(x1 * cs.x - x2 * cs.y);
;           kp[32 + r] = f2bf(x2 * cs.x + x1 * cs.y);
;           if (r < 8) wi[(size_t)(m0 + rl) * 8 + r] = acc[2][i] * 0.044194173824159216f;
;         }
.LBB0_957:
	s_cmp_gt_u32 s4, 23
	s_cbranch_scc0 .LBB0_995
	v_add_u32_e32 v65, s31, v155
	v_add_u32_e32 v64, s5, v155
	s_cmp_gt_u32 s4, 27
	v_lshl_or_b32 v66, v65, 5, v128
	v_ashrrev_i32_e32 v65, 31, v64
	s_cbranch_scc0 .LBB0_992
	v_mov_b32_e32 v67, 0
	v_lshl_add_u64 v[202:203], v[66:67], 3, s[16:17]
	s_mov_b64 s[6:7], 0x800
	v_lshl_add_u64 v[204:205], v[202:203], 0, s[6:7]
	v_lshl_add_u64 v[206:207], v[204:205], 0, s[6:7]
	v_lshl_add_u64 v[208:209], v[206:207], 0, s[6:7]
	global_load_dwordx2 v[92:93], v[202:203], off
	global_load_dwordx2 v[94:95], v[202:203], off offset:256
	global_load_dwordx2 v[96:97], v[202:203], off offset:512
	global_load_dwordx2 v[98:99], v[202:203], off offset:768
	global_load_dwordx2 v[100:101], v[204:205], off
	global_load_dwordx2 v[102:103], v[204:205], off offset:256
	global_load_dwordx2 v[104:105], v[204:205], off offset:512
	global_load_dwordx2 v[106:107], v[204:205], off offset:768
	global_load_dwordx2 v[108:109], v[206:207], off
	global_load_dwordx2 v[110:111], v[206:207], off offset:256
	global_load_dwordx2 v[112:113], v[206:207], off offset:512
	global_load_dwordx2 v[114:115], v[206:207], off offset:768
	global_load_dwordx2 v[116:117], v[208:209], off
	global_load_dwordx2 v[118:119], v[208:209], off offset:256
	global_load_dwordx2 v[120:121], v[208:209], off offset:512
	global_load_dwordx2 v[122:123], v[208:209], off offset:768
	v_lshlrev_b64 v[70:71], 7, v[64:65]
	v_lshl_add_u64 v[210:211], v[132:133], 0, v[70:71]
	v_lshlrev_b64 v[68:69], 5, v[64:65]
	v_lshl_add_u64 v[212:213], v[134:135], 0, v[68:69]
	s_waitcnt vmcnt(15)
	v_mul_f32_e32 v124, v16, v93
	v_mul_f32_e32 v125, v48, v93
	v_fma_f32 v124, v48, v92, -v124
	v_fmac_f32_e32 v125, v16, v92
	v_cvt_pk_bf16_f32 v124, v124, v124
	v_cvt_pk_bf16_f32 v125, v125, v125
	global_store_short v[210:211], v124, off
	global_store_short v[210:211], v125, off offset:64
	s_waitcnt vmcnt(16)
	v_mul_f32_e32 v126, v17, v95
	v_mul_f32_e32 v127, v49, v95
	v_fma_f32 v126, v49, v94, -v126
	v_fmac_f32_e32 v127, v17, v94
	v_cvt_pk_bf16_f32 v126, v126, v126
	v_cvt_pk_bf16_f32 v127, v127, v127
	global_store_short v[210:211], v126, off offset:128
	global_store_short v[210:211], v127, off offset:192
	s_waitcnt vmcnt(17)
	v_mul_f32_e32 v124, v18, v97
	v_mul_f32_e32 v125, v50, v97
	v_fma_f32 v124, v50, v96, -v124
	v_fmac_f32_e32 v125, v18, v96
	v_cvt_pk_bf16_f32 v124, v124, v124
	v_cvt_pk_bf16_f32 v125, v125, v125
	global_store_short v[210:211], v124, off offset:256
	global_store_short v[210:211], v125, off offset:320
	s_waitcnt vmcnt(18)
	v_mul_f32_e32 v126, v19, v99
	v_mul_f32_e32 v127, v51, v99
	v_fma_f32 v126, v51, v98, -v126
	v_fmac_f32_e32 v127, v19, v98
	v_cvt_pk_bf16_f32 v126, v126, v126
	v_cvt_pk_bf16_f32 v127, v127, v127
	global_store_short v[210:211], v126, off offset:384
	global_store_short v[210:211], v127, off offset:448
	s_waitcnt vmcnt(19)
	v_mul_f32_e32 v124, v20, v101
	v_mul_f32_e32 v125, v52, v101
	v_fma_f32 v124, v52, v100, -v124
	v_fmac_f32_e32 v125, v20, v100
	v_cvt_pk_bf16_f32 v124, v124, v124
	v_cvt_pk_bf16_f32 v125, v125, v125
	global_store_short v[210:211], v124, off offset:1024
	global_store_short v[210:211], v125, off offset:1088
	s_waitcnt vmcnt(20)
	v_mul_f32_e32 v126, v21, v103
	v_mul_f32_e32 v127, v53, v103
	v_fma_f32 v126, v53, v102, -v126
	v_fmac_f32_e32 v127, v21, v102
	v_cvt_pk_bf16_f32 v126, v126, v126
	v_cvt_pk_bf16_f32 v127, v127, v127
	global_store_short v[210:211], v126, off offset:1152
	global_store_short v[210:211], v127, off offset:1216
	s_waitcnt vmcnt(21)
	v_mul_f32_e32 v124, v22, v105
	v_mul_f32_e32 v125, v54, v105
	v_fma_f32 v124, v54, v104, -v124
	v_fmac_f32_e32 v125, v22, v104
	v_cvt_pk_bf16_f32 v124, v124, v124
	v_cvt_pk_bf16_f32 v125, v125, v125
	global_store_short v[210:211], v124, off offset:1280
	global_store_short v[210:211], v125, off offset:1344
	s_waitcnt vmcnt(22)
	v_mul_f32_e32 v126, v23, v107
	v_mul_f32_e32 v127, v55, v107
	v_fma_f32 v126, v55, v106, -v126
	v_fmac_f32_e32 v127, v23, v106
	v_cvt_pk_bf16_f32 v126, v126, v126
	v_cvt_pk_bf16_f32 v127, v127, v127
	global_store_short v[210:211], v126, off offset:1408
	global_store_short v[210:211], v127, off offset:1472
	s_waitcnt vmcnt(23)
; DI bf16 f2bf(float a) { return (bf16)(pack2(a, 0.f) & 0xffffu); }
; DI int crow(int i, int g) { return (i & 3) + 8 * (i >> 2) + 4 * g; }
;     ...
; #pragma unroll
;         for (int i = 0; i < 16; ++i) {
;           int rl = 32 * w + crow(i, g);
;           int s = (m0 & 2047) + rl;
;           float2 cs = t64[s * 32 + r];
;           float x1 = acc[0][i], x2 = acc[1][i];
;           bf16* kp = ki + (size_t)(m0 + rl) * 64;
;           kp[r] = f2bf(x1 * cs.x - x2 * cs.y);
;           kp[32 + r] = f2bf(x2 * cs.x + x1 * cs.y);
;           if (r < 8) wi[(size_t)(m0 + rl) * 8 + r] = acc[2][i] * 0.044194173824159216f;
;         }
	v_mul_f32_e32 v124, v24, v109
	v_mul_f32_e32 v125, v56, v109
	v_fma_f32 v124, v56, v108, -v124
	v_fmac_f32_e32 v125, v24, v108
	v_cvt_pk_bf16_f32 v124, v124, v124
	v_cvt_pk_bf16_f32 v125, v125, v125
	global_store_short v[210:211], v124, off offset:2048
	global_store_short v[210:211], v125, off offset:2112
	s_waitcnt vmcnt(24)
	v_mul_f32_e32 v126, v25, v111
	v_mul_f32_e32 v127, v57, v111
	v_fma_f32 v126, v57, v110, -v126
	v_fmac_f32_e32 v127, v25, v110
	v_cvt_pk_bf16_f32 v126, v126, v126
	v_cvt_pk_bf16_f32 v127, v127, v127
	global_store_short v[210:211], v126, off offset:2176
	global_store_short v[210:211], v127, off offset:2240
	s_waitcnt vmcnt(25)
	v_mul_f32_e32 v124, v26, v113
	v_mul_f32_e32 v125, v58, v113
	v_fma_f32 v124, v58, v112, -v124
	v_fmac_f32_e32 v125, v26, v112
	v_cvt_pk_bf16_f32 v124, v124, v124
	v_cvt_pk_bf16_f32 v125, v125, v125
	global_store_short v[210:211], v124, off offset:2304
	global_store_short v[210:211], v125, off offset:2368
	s_waitcnt vmcnt(26)
	v_mul_f32_e32 v126, v27, v115
	v_mul_f32_e32 v127, v59, v115
	v_fma_f32 v126, v59, v114, -v126
	v_fmac_f32_e32 v127, v27, v114
	v_cvt_pk_bf16_f32 v126, v126, v126
	v_cvt_pk_bf16_f32 v127, v127, v127
	global_store_short v[210:211], v126, off offset:2432
	global_store_short v[210:211], v127, off offset:2496
	s_waitcnt vmcnt(27)
	v_mul_f32_e32 v124, v28, v117
	v_mul_f32_e32 v125, v60, v117
	v_fma_f32 v124, v60, v116, -v124
	v_fmac_f32_e32 v125, v28, v116
	v_cvt_pk_bf16_f32 v124, v124, v124
	v_cvt_pk_bf16_f32 v125, v125, v125
	global_store_short v[210:211], v124, off offset:3072
	global_store_short v[210:211], v125, off offset:3136
	s_waitcnt vmcnt(28)
	v_mul_f32_e32 v126, v29, v119
	v_mul_f32_e32 v127, v61, v119
	v_fma_f32 v126, v61, v118, -v126
	v_fmac_f32_e32 v127, v29, v118
	v_cvt_pk_bf16_f32 v126, v126, v126
	v_cvt_pk_bf16_f32 v127, v127, v127
	global_store_short v[210:211], v126, off offset:3200
	global_store_short v[210:211], v127, off offset:3264
	s_waitcnt vmcnt(29)
	v_mul_f32_e32 v124, v30, v121
	v_mul_f32_e32 v125, v62, v121
	v_fma_f32 v124, v62, v120, -v124
	v_fmac_f32_e32 v125, v30, v120
	v_cvt_pk_bf16_f32 v124, v124, v124
	v_cvt_pk_bf16_f32 v125, v125, v125
	global_store_short v[210:211], v124, off offset:3328
	global_store_short v[210:211], v125, off offset:3392
	s_waitcnt vmcnt(30)
	v_mul_f32_e32 v126, v31, v123
	v_mul_f32_e32 v127, v63, v123
	v_fma_f32 v126, v63, v122, -v126
	v_fmac_f32_e32 v127, v31, v122
	v_cvt_pk_bf16_f32 v126, v126, v126
	v_cvt_pk_bf16_f32 v127, v127, v127
	global_store_short v[210:211], v126, off offset:3456
	global_store_short v[210:211], v127, off offset:3520
	v_mul_f32_e32 v92, 0x3d3504f3, v32
	v_mul_f32_e32 v93, 0x3d3504f3, v33
	v_mul_f32_e32 v94, 0x3d3504f3, v34
	v_mul_f32_e32 v95, 0x3d3504f3, v35
	v_mul_f32_e32 v96, 0x3d3504f3, v36
	v_mul_f32_e32 v97, 0x3d3504f3, v37
	v_mul_f32_e32 v98, 0x3d3504f3, v38
	v_mul_f32_e32 v99, 0x3d3504f3, v39
	v_mul_f32_e32 v100, 0x3d3504f3, v40
	v_mul_f32_e32 v101, 0x3d3504f3, v41
	v_mul_f32_e32 v102, 0x3d3504f3, v42
	v_mul_f32_e32 v103, 0x3d3504f3, v43
	v_mul_f32_e32 v104, 0x3d3504f3, v44
	v_mul_f32_e32 v105, 0x3d3504f3, v45
	v_mul_f32_e32 v106, 0x3d3504f3, v46
	v_mul_f32_e32 v107, 0x3d3504f3, v47
	s_and_saveexec_b64 s[28:29], s[8:9]
	global_store_dword v[212:213], v92, off
	global_store_dword v[212:213], v93, off offset:32
	global_store_dword v[212:213], v94, off offset:64
	global_store_dword v[212:213], v95, off offset:96
	global_store_dword v[212:213], v96, off offset:256
	global_store_dword v[212:213], v97, off offset:288
	global_store_dword v[212:213], v98, off offset:320
	global_store_dword v[212:213], v99, off offset:352
	global_store_dword v[212:213], v100, off offset:512
	global_store_dword v[212:213], v101, off offset:544
	global_store_dword v[212:213], v102, off offset:576
	global_store_dword v[212:213], v103, off offset:608
	global_store_dword v[212:213], v104, off offset:768
	global_store_dword v[212:213], v105, off offset:800
	global_store_dword v[212:213], v106, off offset:832
	global_store_dword v[212:213], v107, off offset:864

; DI bf16 f2bf(float a) { return (bf16)(pack2(a, 0.f) & 0xffffu); }
; DI int crow(int i, int g) { return (i & 3) + 8 * (i >> 2) + 4 * g; }
;     ...
;       } else if (nt < 28) {
;         bf16* qi = (bf16*)(ws + OFF_QI);
; #pragma unroll
;         for (int jp = 0; jp < 2; ++jp)
; #pragma unroll
;           for (int i = 0; i < 16; ++i) {
;             int rl = 32 * w + crow(i, g);
;             int s = (m0 & 2047) + rl;
;             float2 cs = t64[s * 32 + r];
;             float x1 = acc[2 * jp][i], x2 = acc[2 * jp + 1][i];
;             int ih = 2 * (nt - 24) + jp;
;             bf16* qp = qi + ((size_t)(m0 + rl) * 8 + ih) * 64;
;             qp[r] = f2bf(x1 * cs.x - x2 * cs.y);
;             qp[32 + r] = f2bf(x2 * cs.x + x1 * cs.y);
;           }
.LBB0_992:
	s_and_b64 vcc, exec, s[28:29]
	s_cbranch_vccz .LBB0_994
	v_mov_b32_e32 v67, 0
	v_lshl_add_u64 v[202:203], v[66:67], 3, s[16:17]
	s_mov_b64 s[6:7], 0x800
	v_lshl_add_u64 v[204:205], v[202:203], 0, s[6:7]
	v_lshl_add_u64 v[206:207], v[204:205], 0, s[6:7]
	v_lshl_add_u64 v[208:209], v[206:207], 0, s[6:7]
	global_load_dwordx2 v[92:93], v[202:203], off
	global_load_dwordx2 v[94:95], v[202:203], off offset:256
	global_load_dwordx2 v[96:97], v[202:203], off offset:512
	global_load_dwordx2 v[98:99], v[202:203], off offset:768
	global_load_dwordx2 v[100:101], v[204:205], off
	global_load_dwordx2 v[102:103], v[204:205], off offset:256
	global_load_dwordx2 v[104:105], v[204:205], off offset:512
	global_load_dwordx2 v[106:107], v[204:205], off offset:768
	global_load_dwordx2 v[108:109], v[206:207], off
	global_load_dwordx2 v[110:111], v[206:207], off offset:256
	global_load_dwordx2 v[112:113], v[206:207], off offset:512
	global_load_dwordx2 v[114:115], v[206:207], off offset:768
	global_load_dwordx2 v[116:117], v[208:209], off
	global_load_dwordx2 v[118:119], v[208:209], off offset:256
	global_load_dwordx2 v[120:121], v[208:209], off offset:512
	global_load_dwordx2 v[122:123], v[208:209], off offset:768
	s_lshl_b32 s6, s4, 1
	s_sub_i32 s14, s6, 48
	s_lshl_b64 s[28:29], s[14:15], 7
	v_lshl_add_u64 v[74:75], v[136:137], 0, s[28:29]
	v_lshlrev_b64 v[64:65], 10, v[64:65]
	v_lshl_add_u64 v[210:211], v[74:75], 0, v[64:65]
	s_mov_b64 s[6:7], 0x2000
	v_lshl_add_u64 v[212:213], v[210:211], 0, s[6:7]
	v_lshl_add_u64 v[214:215], v[212:213], 0, s[6:7]
	v_lshl_add_u64 v[216:217], v[214:215], 0, s[6:7]
	s_waitcnt vmcnt(15)
	v_mul_f32_e32 v124, v16, v93
	v_mul_f32_e32 v125, v48, v93
	v_fma_f32 v124, v48, v92, -v124
	v_fmac_f32_e32 v125, v16, v92
	v_cvt_pk_bf16_f32 v124, v124, v124
	v_cvt_pk_bf16_f32 v125, v125, v125
	v_mul_f32_e32 v126, v0, v93
	v_mul_f32_e32 v127, v32, v93
	v_fma_f32 v126, v32, v92, -v126
	v_fmac_f32_e32 v127, v0, v92
	v_cvt_pk_bf16_f32 v126, v126, v126
	v_cvt_pk_bf16_f32 v127, v127, v127
	global_store_short v[210:211], v124, off
	global_store_short v[210:211], v125, off offset:64
	global_store_short v[210:211], v126, off offset:128
	global_store_short v[210:211], v127, off offset:192
	s_waitcnt vmcnt(18)
	v_mul_f32_e32 v124, v17, v95
	v_mul_f32_e32 v125, v49, v95
	v_fma_f32 v124, v49, v94, -v124
	v_fmac_f32_e32 v125, v17, v94
	v_cvt_pk_bf16_f32 v124, v124, v124
	v_cvt_pk_bf16_f32 v125, v125, v125
	v_mul_f32_e32 v126, v1, v95
	v_mul_f32_e32 v127, v33, v95
	v_fma_f32 v126, v33, v94, -v126
	v_fmac_f32_e32 v127, v1, v94
	v_cvt_pk_bf16_f32 v126, v126, v126
	v_cvt_pk_bf16_f32 v127, v127, v127
	global_store_short v[210:211], v124, off offset:1024
	global_store_short v[210:211], v125, off offset:1088
	global_store_short v[210:211], v126, off offset:1152
	global_store_short v[210:211], v127, off offset:1216
	s_waitcnt vmcnt(21)
	v_mul_f32_e32 v124, v18, v97
	v_mul_f32_e32 v125, v50, v97
	v_fma_f32 v124, v50, v96, -v124
	v_fmac_f32_e32 v125, v18, v96
	v_cvt_pk_bf16_f32 v124, v124, v124
	v_cvt_pk_bf16_f32 v125, v125, v125
	v_mul_f32_e32 v126, v2, v97
	v_mul_f32_e32 v127, v34, v97
	v_fma_f32 v126, v34, v96, -v126
	v_fmac_f32_e32 v127, v2, v96
	v_cvt_pk_bf16_f32 v126, v126, v126
	v_cvt_pk_bf16_f32 v127, v127, v127
	global_store_short v[210:211], v124, off offset:2048
	global_store_short v[210:211], v125, off offset:2112
	global_store_short v[210:211], v126, off offset:2176
	global_store_short v[210:211], v127, off offset:2240
	s_waitcnt vmcnt(24)
	v_mul_f32_e32 v124, v19, v99
	v_mul_f32_e32 v125, v51, v99
	v_fma_f32 v124, v51, v98, -v124
	v_fmac_f32_e32 v125, v19, v98
	v_cvt_pk_bf16_f32 v124, v124, v124
	v_cvt_pk_bf16_f32 v125, v125, v125
	v_mul_f32_e32 v126, v3, v99
	v_mul_f32_e32 v127, v35, v99
	v_fma_f32 v126, v35, v98, -v126
	v_fmac_f32_e32 v127, v3, v98
	v_cvt_pk_bf16_f32 v126, v126, v126
	v_cvt_pk_bf16_f32 v127, v127, v127
	global_store_short v[210:211], v124, off offset:3072
	global_store_short v[210:211], v125, off offset:3136
	global_store_short v[210:211], v126, off offset:3200
	global_store_short v[210:211], v127, off offset:3264
	s_waitcnt vmcnt(27)
	v_mul_f32_e32 v124, v20, v101
	v_mul_f32_e32 v125, v52, v101
	v_fma_f32 v124, v52, v100, -v124
	v_fmac_f32_e32 v125, v20, v100
	v_cvt_pk_bf16_f32 v124, v124, v124
	v_cvt_pk_bf16_f32 v125, v125, v125
	v_mul_f32_e32 v126, v4, v101
	v_mul_f32_e32 v127, v36, v101
	v_fma_f32 v126, v36, v100, -v126
	v_fmac_f32_e32 v127, v4, v100
	v_cvt_pk_bf16_f32 v126, v126, v126
	v_cvt_pk_bf16_f32 v127, v127, v127
	global_store_short v[212:213], v124, off
	global_store_short v[212:213], v125, off offset:64
	global_store_short v[212:213], v126, off offset:128
	global_store_short v[212:213], v127, off offset:192
	s_waitcnt vmcnt(30)
	v_mul_f32_e32 v124, v21, v103
	v_mul_f32_e32 v125, v53, v103
	v_fma_f32 v124, v53, v102, -v124
	v_fmac_f32_e32 v125, v21, v102
	v_cvt_pk_bf16_f32 v124, v124, v124
	v_cvt_pk_bf16_f32 v125, v125, v125
	v_mul_f32_e32 v126, v5, v103
	v_mul_f32_e32 v127, v37, v103
	v_fma_f32 v126, v37, v102, -v126
	v_fmac_f32_e32 v127, v5, v102
	v_cvt_pk_bf16_f32 v126, v126, v126
	v_cvt_pk_bf16_f32 v127, v127, v127
	global_store_short v[212:213], v124, off offset:1024
	global_store_short v[212:213], v125, off offset:1088
	global_store_short v[212:213], v126, off offset:1152
	global_store_short v[212:213], v127, off offset:1216
	s_waitcnt vmcnt(33)
; DI bf16 f2bf(float a) { return (bf16)(pack2(a, 0.f) & 0xffffu); }
; DI int crow(int i, int g) { return (i & 3) + 8 * (i >> 2) + 4 * g; }
;     ...
;         for (int jp = 0; jp < 2; ++jp)
; #pragma unroll
;           for (int i = 0; i < 16; ++i) {
;             int rl = 32 * w + crow(i, g);
;             int s = (m0 & 2047) + rl;
;             float2 cs = t64[s * 32 + r];
;             float x1 = acc[2 * jp][i], x2 = acc[2 * jp + 1][i];
;             int ih = 2 * (nt - 24) + jp;
;             bf16* qp = qi + ((size_t)(m0 + rl) * 8 + ih) * 64;
;             qp[r] = f2bf(x1 * cs.x - x2 * cs.y);
;             qp[32 + r] = f2bf(x2 * cs.x + x1 * cs.y);
;           }
	v_mul_f32_e32 v124, v22, v105
	v_mul_f32_e32 v125, v54, v105
	v_fma_f32 v124, v54, v104, -v124
	v_fmac_f32_e32 v125, v22, v104
	v_cvt_pk_bf16_f32 v124, v124, v124
	v_cvt_pk_bf16_f32 v125, v125, v125
	v_mul_f32_e32 v126, v6, v105
	v_mul_f32_e32 v127, v38, v105
	v_fma_f32 v126, v38, v104, -v126
	v_fmac_f32_e32 v127, v6, v104
	v_cvt_pk_bf16_f32 v126, v126, v126
	v_cvt_pk_bf16_f32 v127, v127, v127
	global_store_short v[212:213], v124, off offset:2048
	global_store_short v[212:213], v125, off offset:2112
	global_store_short v[212:213], v126, off offset:2176
	global_store_short v[212:213], v127, off offset:2240
	s_waitcnt vmcnt(36)
	v_mul_f32_e32 v124, v23, v107
	v_mul_f32_e32 v125, v55, v107
	v_fma_f32 v124, v55, v106, -v124
	v_fmac_f32_e32 v125, v23, v106
	v_cvt_pk_bf16_f32 v124, v124, v124
	v_cvt_pk_bf16_f32 v125, v125, v125
	v_mul_f32_e32 v126, v7, v107
	v_mul_f32_e32 v127, v39, v107
	v_fma_f32 v126, v39, v106, -v126
	v_fmac_f32_e32 v127, v7, v106
	v_cvt_pk_bf16_f32 v126, v126, v126
	v_cvt_pk_bf16_f32 v127, v127, v127
	global_store_short v[212:213], v124, off offset:3072
	global_store_short v[212:213], v125, off offset:3136
	global_store_short v[212:213], v126, off offset:3200
	global_store_short v[212:213], v127, off offset:3264
	s_waitcnt vmcnt(39)
	v_mul_f32_e32 v124, v24, v109
	v_mul_f32_e32 v125, v56, v109
	v_fma_f32 v124, v56, v108, -v124
	v_fmac_f32_e32 v125, v24, v108
	v_cvt_pk_bf16_f32 v124, v124, v124
	v_cvt_pk_bf16_f32 v125, v125, v125
	v_mul_f32_e32 v126, v8, v109
	v_mul_f32_e32 v127, v40, v109
	v_fma_f32 v126, v40, v108, -v126
	v_fmac_f32_e32 v127, v8, v108
	v_cvt_pk_bf16_f32 v126, v126, v126
	v_cvt_pk_bf16_f32 v127, v127, v127
	global_store_short v[214:215], v124, off
	global_store_short v[214:215], v125, off offset:64
	global_store_short v[214:215], v126, off offset:128
	global_store_short v[214:215], v127, off offset:192
	s_waitcnt vmcnt(42)
	v_mul_f32_e32 v124, v25, v111
	v_mul_f32_e32 v125, v57, v111
	v_fma_f32 v124, v57, v110, -v124
	v_fmac_f32_e32 v125, v25, v110
	v_cvt_pk_bf16_f32 v124, v124, v124
	v_cvt_pk_bf16_f32 v125, v125, v125
	v_mul_f32_e32 v126, v9, v111
	v_mul_f32_e32 v127, v41, v111
	v_fma_f32 v126, v41, v110, -v126
	v_fmac_f32_e32 v127, v9, v110
	v_cvt_pk_bf16_f32 v126, v126, v126
	v_cvt_pk_bf16_f32 v127, v127, v127
	global_store_short v[214:215], v124, off offset:1024
	global_store_short v[214:215], v125, off offset:1088
	global_store_short v[214:215], v126, off offset:1152
	global_store_short v[214:215], v127, off offset:1216
	s_waitcnt vmcnt(45)
	v_mul_f32_e32 v124, v26, v113
	v_mul_f32_e32 v125, v58, v113
	v_fma_f32 v124, v58, v112, -v124
	v_fmac_f32_e32 v125, v26, v112
	v_cvt_pk_bf16_f32 v124, v124, v124
	v_cvt_pk_bf16_f32 v125, v125, v125
	v_mul_f32_e32 v126, v10, v113
	v_mul_f32_e32 v127, v42, v113
	v_fma_f32 v126, v42, v112, -v126
	v_fmac_f32_e32 v127, v10, v112
	v_cvt_pk_bf16_f32 v126, v126, v126
	v_cvt_pk_bf16_f32 v127, v127, v127
	global_store_short v[214:215], v124, off offset:2048
	global_store_short v[214:215], v125, off offset:2112
	global_store_short v[214:215], v126, off offset:2176
	global_store_short v[214:215], v127, off offset:2240
	s_waitcnt vmcnt(48)
	v_mul_f32_e32 v124, v27, v115
	v_mul_f32_e32 v125, v59, v115
	v_fma_f32 v124, v59, v114, -v124
	v_fmac_f32_e32 v125, v27, v114
	v_cvt_pk_bf16_f32 v124, v124, v124
	v_cvt_pk_bf16_f32 v125, v125, v125
	v_mul_f32_e32 v126, v11, v115
	v_mul_f32_e32 v127, v43, v115
	v_fma_f32 v126, v43, v114, -v126
	v_fmac_f32_e32 v127, v11, v114
	v_cvt_pk_bf16_f32 v126, v126, v126
	v_cvt_pk_bf16_f32 v127, v127, v127
	global_store_short v[214:215], v124, off offset:3072
	global_store_short v[214:215], v125, off offset:3136
	global_store_short v[214:215], v126, off offset:3200
	global_store_short v[214:215], v127, off offset:3264
	s_waitcnt vmcnt(51)
	v_mul_f32_e32 v124, v28, v117
	v_mul_f32_e32 v125, v60, v117
	v_fma_f32 v124, v60, v116, -v124
	v_fmac_f32_e32 v125, v28, v116
	v_cvt_pk_bf16_f32 v124, v124, v124
	v_cvt_pk_bf16_f32 v125, v125, v125
	v_mul_f32_e32 v126, v12, v117
	v_mul_f32_e32 v127, v44, v117
	v_fma_f32 v126, v44, v116, -v126
	v_fmac_f32_e32 v127, v12, v116
	v_cvt_pk_bf16_f32 v126, v126, v126
	v_cvt_pk_bf16_f32 v127, v127, v127
	global_store_short v[216:217], v124, off
	global_store_short v[216:217], v125, off offset:64
	global_store_short v[216:217], v126, off offset:128
	global_store_short v[216:217], v127, off offset:192
	s_waitcnt vmcnt(54)
	v_mul_f32_e32 v124, v29, v119
	v_mul_f32_e32 v125, v61, v119
	v_fma_f32 v124, v61, v118, -v124
	v_fmac_f32_e32 v125, v29, v118
	v_cvt_pk_bf16_f32 v124, v124, v124
	v_cvt_pk_bf16_f32 v125, v125, v125
	v_mul_f32_e32 v126, v13, v119
	v_mul_f32_e32 v127, v45, v119
	v_fma_f32 v126, v45, v118, -v126
	v_fmac_f32_e32 v127, v13, v118
	v_cvt_pk_bf16_f32 v126, v126, v126
	v_cvt_pk_bf16_f32 v127, v127, v127
	global_store_short v[216:217], v124, off offset:1024
	global_store_short v[216:217], v125, off offset:1088
	global_store_short v[216:217], v126, off offset:1152
	global_store_short v[216:217], v127, off offset:1216
	s_waitcnt vmcnt(57)
	v_mul_f32_e32 v124, v30, v121
	v_mul_f32_e32 v125, v62, v121
	v_fma_f32 v124, v62, v120, -v124
	v_fmac_f32_e32 v125, v30, v120
	v_cvt_pk_bf16_f32 v124, v124, v124
	v_cvt_pk_bf16_f32 v125, v125, v125
	v_mul_f32_e32 v126, v14, v121
	v_mul_f32_e32 v127, v46, v121
	v_fma_f32 v126, v46, v120, -v126
	v_fmac_f32_e32 v127, v14, v120
	v_cvt_pk_bf16_f32 v126, v126, v126
	v_cvt_pk_bf16_f32 v127, v127, v127
	global_store_short v[216:217], v124, off offset:2048
	global_store_short v[216:217], v125, off offset:2112
	global_store_short v[216:217], v126, off offset:2176
	global_store_short v[216:217], v127, off offset:2240
	s_waitcnt vmcnt(60)
	v_mul_f32_e32 v124, v31, v123
	v_mul_f32_e32 v125, v63, v123
	v_fma_f32 v124, v63, v122, -v124
	v_fmac_f32_e32 v125, v31, v122
	v_cvt_pk_bf16_f32 v124, v124, v124
	v_cvt_pk_bf16_f32 v125, v125, v125
	v_mul_f32_e32 v126, v15, v123
	v_mul_f32_e32 v127, v47, v123
	v_fma_f32 v126, v47, v122, -v126
	v_fmac_f32_e32 v127, v15, v122
	v_cvt_pk_bf16_f32 v126, v126, v126
	v_cvt_pk_bf16_f32 v127, v127, v127
	global_store_short v[216:217], v124, off offset:3072
	global_store_short v[216:217], v125, off offset:3136
	global_store_short v[216:217], v126, off offset:3200
	global_store_short v[216:217], v127, off offset:3264
